# attention QK^T blocks: ds_read->wait->MFMA serial chains replaced by 3/4-deep read rings with counted lgkmcnt (attnA loop x4, attnC loop)
# baseline (speedup 1.0000x reference)
.LBB0_1057:
	v_cmp_le_i32_e32 vcc, s12, v187
	s_and_saveexec_b64 s[10:11], vcc
	s_cbranch_execz .LBB0_1059
	s_lshl_b32 s12, s12, 15
	s_and_b32 s12, s12, 0x8000
	s_add_i32 s12, s80, s12
	v_add3_u32 v0, s12, v191, v188
	ds_read_b128 v[2:5], v0
	ds_read_b128 v[8:11], v0 offset:8192
	v_add3_u32 v0, s12, v192, v188
	ds_read_b128 v[12:15], v0
	s_waitcnt lgkmcnt(2)
	v_mfma_f32_32x32x16_bf16 v[112:127], v[2:5], v[156:159], v[16:31]
	ds_read_b128 v[2:5], v0 offset:8192
	s_waitcnt lgkmcnt(2)
	v_mfma_f32_32x32x16_bf16 v[96:111], v[8:11], v[156:159], v[16:31]
	v_add3_u32 v0, s12, v193, v188
	ds_read_b128 v[8:11], v0
	s_waitcnt lgkmcnt(2)
	v_mfma_f32_32x32x16_bf16 v[112:127], v[12:15], v[128:131], v[112:127]
	ds_read_b128 v[12:15], v0 offset:8192
	s_waitcnt lgkmcnt(2)
	v_mfma_f32_32x32x16_bf16 v[96:111], v[2:5], v[128:131], v[96:111]
	v_add3_u32 v0, s12, v194, v188
	ds_read_b128 v[2:5], v0
	s_waitcnt lgkmcnt(2)
	v_mfma_f32_32x32x16_bf16 v[112:127], v[8:11], v[132:135], v[112:127]
	ds_read_b128 v[8:11], v0 offset:8192
	s_waitcnt lgkmcnt(2)
	v_mfma_f32_32x32x16_bf16 v[96:111], v[12:15], v[132:135], v[96:111]
	v_add3_u32 v0, s12, v195, v188
	ds_read_b128 v[12:15], v0
	s_waitcnt lgkmcnt(2)
	v_mfma_f32_32x32x16_bf16 v[112:127], v[2:5], v[136:139], v[112:127]
	ds_read_b128 v[2:5], v0 offset:8192
	s_waitcnt lgkmcnt(2)
	v_mfma_f32_32x32x16_bf16 v[96:111], v[8:11], v[136:139], v[96:111]
	v_add3_u32 v0, s12, v196, v188
	ds_read_b128 v[8:11], v0
	s_waitcnt lgkmcnt(2)
	v_mfma_f32_32x32x16_bf16 v[112:127], v[12:15], v[140:143], v[112:127]
	ds_read_b128 v[12:15], v0 offset:8192
	s_waitcnt lgkmcnt(2)
	v_mfma_f32_32x32x16_bf16 v[96:111], v[2:5], v[140:143], v[96:111]
	v_add3_u32 v0, s12, v197, v188
	ds_read_b128 v[2:5], v0
	s_waitcnt lgkmcnt(2)
	v_mfma_f32_32x32x16_bf16 v[112:127], v[8:11], v[144:147], v[112:127]
	ds_read_b128 v[8:11], v0 offset:8192
	s_waitcnt lgkmcnt(2)
	v_mfma_f32_32x32x16_bf16 v[96:111], v[12:15], v[144:147], v[96:111]
	v_add3_u32 v0, s12, v198, v188
	ds_read_b128 v[12:15], v0
	s_waitcnt lgkmcnt(2)
	v_mfma_f32_32x32x16_bf16 v[112:127], v[2:5], v[148:151], v[112:127]
	ds_read_b128 v[2:5], v0 offset:8192
	s_waitcnt lgkmcnt(2)
	v_mfma_f32_32x32x16_bf16 v[96:111], v[8:11], v[148:151], v[96:111]
	s_waitcnt lgkmcnt(1)
	v_mfma_f32_32x32x16_bf16 v[112:127], v[12:15], v[152:155], v[112:127]
	s_waitcnt lgkmcnt(0)
	v_mfma_f32_32x32x16_bf16 v[96:111], v[2:5], v[152:155], v[96:111]
	v_lshrrev_b32_e32 v0, v189, v168
	v_and_b32_e32 v8, 4, v0
	v_and_b32_e32 v9, 8, v0
	v_and_b32_e32 v10, 0x100, v0
	v_and_b32_e32 v11, 0x200, v0
	s_nop 4
	v_exp_f32_e32 v2, v112
	v_and_b32_e32 v3, 1, v0
	v_cmp_eq_u32_e32 vcc, 1, v3
	v_exp_f32_e32 v3, v113
	v_and_b32_e32 v5, 2, v0
	v_cndmask_b32_e32 v2, 0, v2, vcc
	v_cmp_ne_u32_e32 vcc, 0, v5
	v_add_f32_e32 v4, 0, v2
	s_nop 0
	v_cndmask_b32_e32 v3, 0, v3, vcc
	v_add_f32_e32 v5, v3, v4
	v_exp_f32_e32 v4, v114
	v_cmp_ne_u32_e32 vcc, 0, v8
	v_cvt_pk_bf16_f32 v2, v2, v3
	s_nop 0
	v_cndmask_b32_e32 v4, 0, v4, vcc
	v_add_f32_e32 v8, v4, v5
	v_exp_f32_e32 v5, v115
	v_cmp_ne_u32_e32 vcc, 0, v9
	v_exp_f32_e32 v9, v116
	s_nop 0
	v_cndmask_b32_e32 v5, 0, v5, vcc
	v_cmp_ne_u32_e32 vcc, 0, v10
	v_exp_f32_e32 v10, v117
	v_add_f32_e32 v8, v5, v8
	v_cndmask_b32_e32 v9, 0, v9, vcc
	v_cmp_ne_u32_e32 vcc, 0, v11
	v_and_b32_e32 v11, 0x400, v0
	v_add_f32_e32 v8, v9, v8
	v_cndmask_b32_e32 v15, 0, v10, vcc
	v_exp_f32_e32 v10, v118
	v_cmp_ne_u32_e32 vcc, 0, v11
	v_and_b32_e32 v11, 0x800, v0
	v_add_f32_e32 v8, v15, v8
	v_cndmask_b32_e32 v113, 0, v10, vcc
	v_exp_f32_e32 v10, v119
	v_cmp_ne_u32_e32 vcc, 0, v11
	v_and_b32_e32 v11, 0x10000, v0
	v_add_f32_e32 v8, v113, v8
	v_cndmask_b32_e32 v115, 0, v10, vcc
	v_exp_f32_e32 v10, v120
	v_cmp_ne_u32_e32 vcc, 0, v11
	v_and_b32_e32 v11, 0x20000, v0
	v_add_f32_e32 v8, v115, v8
	v_cndmask_b32_e32 v112, 0, v10, vcc
	v_exp_f32_e32 v10, v121
	v_cmp_ne_u32_e32 vcc, 0, v11
	v_and_b32_e32 v11, 0x40000, v0
	v_add_f32_e32 v8, v112, v8
	v_cndmask_b32_e32 v117, 0, v10, vcc
	v_exp_f32_e32 v10, v122
	v_cmp_ne_u32_e32 vcc, 0, v11
	v_and_b32_e32 v11, 0x80000, v0
	v_add_f32_e32 v8, v117, v8
	v_cndmask_b32_e32 v122, 0, v10, vcc
	v_exp_f32_e32 v10, v123
	v_cmp_ne_u32_e32 vcc, 0, v11
	v_and_b32_e32 v11, 0x1000000, v0
	v_add_f32_e32 v8, v122, v8
	v_cndmask_b32_e32 v123, 0, v10, vcc
	v_exp_f32_e32 v10, v124
	v_cmp_ne_u32_e32 vcc, 0, v11
	v_and_b32_e32 v11, 0x2000000, v0
	v_add_f32_e32 v8, v123, v8
	v_cndmask_b32_e32 v124, 0, v10, vcc
	v_exp_f32_e32 v10, v125
	v_cmp_ne_u32_e32 vcc, 0, v11
	v_and_b32_e32 v11, 0x4000000, v0
	v_add_f32_e32 v8, v124, v8
	v_cndmask_b32_e32 v125, 0, v10, vcc
	v_exp_f32_e32 v10, v126
	v_cmp_ne_u32_e32 vcc, 0, v11
	v_and_b32_e32 v0, 0x8000000, v0
	v_add_f32_e32 v8, v125, v8
	v_cndmask_b32_e32 v126, 0, v10, vcc
	v_exp_f32_e32 v10, v127
	v_cmp_ne_u32_e32 vcc, 0, v0
	v_add_f32_e32 v8, v126, v8
	v_lshrrev_b32_e32 v118, v189, v169
	v_cndmask_b32_e32 v127, 0, v10, vcc
	v_add_f32_e32 v0, v127, v8
	v_exp_f32_e32 v8, v96
	v_and_b32_e32 v10, 1, v118
	v_cmp_eq_u32_e32 vcc, 1, v10
	v_and_b32_e32 v10, 2, v118
	v_and_b32_e32 v11, 0x20000, v118
	v_cndmask_b32_e32 v114, 0, v8, vcc
	v_exp_f32_e32 v8, v97
	v_cmp_ne_u32_e32 vcc, 0, v10
	v_and_b32_e32 v10, 4, v118
	v_and_b32_e32 v12, 0x40000, v118
	v_cndmask_b32_e32 v116, 0, v8, vcc
	v_exp_f32_e32 v8, v98
	v_cmp_ne_u32_e32 vcc, 0, v10
	v_and_b32_e32 v10, 8, v118
	v_and_b32_e32 v13, 0x80000, v118
	v_cndmask_b32_e32 v98, 0, v8, vcc
	v_exp_f32_e32 v8, v99
	v_cmp_ne_u32_e32 vcc, 0, v10
	v_and_b32_e32 v10, 0x100, v118
	v_and_b32_e32 v14, 0x1000000, v118
	v_cndmask_b32_e32 v99, 0, v8, vcc
	v_exp_f32_e32 v8, v100
	v_cmp_ne_u32_e32 vcc, 0, v10
	v_and_b32_e32 v10, 0x200, v118
	v_and_b32_e32 v96, 0x2000000, v118
	v_cndmask_b32_e32 v100, 0, v8, vcc
	v_exp_f32_e32 v8, v101
	v_cmp_ne_u32_e32 vcc, 0, v10
	v_and_b32_e32 v10, 0x400, v118
	v_and_b32_e32 v97, 0x4000000, v118
	v_cndmask_b32_e32 v101, 0, v8, vcc
	v_exp_f32_e32 v8, v102
	v_cmp_ne_u32_e32 vcc, 0, v10
	v_and_b32_e32 v10, 0x800, v118
	v_cvt_pk_bf16_f32 v3, v4, v5
	v_cndmask_b32_e32 v102, 0, v8, vcc
	v_exp_f32_e32 v8, v103
	v_cmp_ne_u32_e32 vcc, 0, v10
	v_and_b32_e32 v10, 0x10000, v118
	v_cvt_pk_bf16_f32 v4, v9, v15
	v_cndmask_b32_e32 v103, 0, v8, vcc
	v_exp_f32_e32 v8, v104
	v_cmp_ne_u32_e32 vcc, 0, v10
	v_exp_f32_e32 v10, v105
	v_and_b32_e32 v104, 0x8000000, v118
	v_cndmask_b32_e32 v8, 0, v8, vcc
	v_cmp_ne_u32_e32 vcc, 0, v11
	v_exp_f32_e32 v11, v106
	v_cvt_pk_bf16_f32 v5, v113, v115
	v_cndmask_b32_e32 v10, 0, v10, vcc
	v_cmp_ne_u32_e32 vcc, 0, v12
	v_exp_f32_e32 v12, v107
	v_add_f32_e32 v0, v114, v0
	v_cndmask_b32_e32 v11, 0, v11, vcc
	v_cmp_ne_u32_e32 vcc, 0, v13
	v_exp_f32_e32 v13, v108
	v_add_f32_e32 v0, v116, v0
	v_cndmask_b32_e32 v12, 0, v12, vcc
	v_cmp_ne_u32_e32 vcc, 0, v14
	v_exp_f32_e32 v14, v109
	v_add_f32_e32 v0, v98, v0
	v_cndmask_b32_e32 v13, 0, v13, vcc
	v_cmp_ne_u32_e32 vcc, 0, v96
	v_exp_f32_e32 v96, v110
	v_add_f32_e32 v0, v99, v0
	v_cndmask_b32_e32 v14, 0, v14, vcc
	v_cmp_ne_u32_e32 vcc, 0, v97
	v_exp_f32_e32 v97, v111
	v_add_f32_e32 v0, v100, v0
	v_cndmask_b32_e32 v96, 0, v96, vcc
	v_cmp_ne_u32_e32 vcc, 0, v104
	v_add_u32_e32 v104, s12, v186
	v_add_u32_e32 v9, v104, v190
	v_add_u32_e32 v15, v9, v199
	ds_read2st64_b64 v[106:109], v15 offset0:32 offset1:40
	v_add3_u32 v105, v104, v200, v190
	ds_read_b64 v[120:121], v105 offset:16384
	v_add_u32_e32 v105, v9, v200
	ds_read_b64 v[110:111], v105 offset:28672
	s_waitcnt lgkmcnt(2)
	v_mov_b32_e32 v118, v106
	v_mov_b32_e32 v119, v107
	v_mov_b32_e32 v106, v108
	v_mov_b32_e32 v107, v109
	s_waitcnt lgkmcnt(1)
	v_mfma_f32_32x32x16_bf16 v[80:95], v[118:121], v[2:5], v[80:95]
	ds_read2st64_b64 v[118:121], v105 offset0:40 offset1:48
	v_add_f32_e32 v0, v101, v0
	v_add_f32_e32 v0, v102, v0
	v_add_f32_e32 v0, v103, v0
	v_add_f32_e32 v0, v8, v0
	s_waitcnt lgkmcnt(0)
	v_mov_b32_e32 v108, v118
	v_mov_b32_e32 v109, v119
	v_add_f32_e32 v0, v10, v0
	v_add_f32_e32 v0, v11, v0
	v_mfma_f32_32x32x16_bf16 v[64:79], v[106:109], v[2:5], v[64:79]
	ds_read2st64_b64 v[106:109], v15 offset0:48 offset1:56
	v_add3_u32 v15, v104, v201, v190
	v_add_f32_e32 v0, v12, v0
	v_add_f32_e32 v0, v13, v0
	v_add_f32_e32 v0, v14, v0
	s_waitcnt lgkmcnt(0)
	v_mov_b32_e32 v118, v106
	v_mov_b32_e32 v119, v107
	ds_read_b64 v[106:107], v15 offset:16384
	v_add3_u32 v15, v104, v202, v190
	v_mfma_f32_32x32x16_bf16 v[32:47], v[108:111], v[2:5], v[32:47]
	ds_read_b64 v[108:109], v15 offset:16384
	v_add_u32_e32 v15, v9, v201
	v_add_u32_e32 v105, v9, v202
	v_cndmask_b32_e32 v97, 0, v97, vcc
	v_add_f32_e32 v0, v96, v0
	v_add_f32_e32 v0, v97, v0
	v_add_f32_e32 v219, v219, v0
	v_mfma_f32_32x32x16_bf16 v[48:63], v[118:121], v[2:5], v[48:63]
	v_cvt_pk_bf16_f32 v2, v112, v117
	v_cvt_pk_bf16_f32 v3, v122, v123
	v_cvt_pk_bf16_f32 v4, v124, v125
	v_cvt_pk_bf16_f32 v5, v126, v127
	ds_read2st64_b64 v[110:113], v105 offset0:40 offset1:48
	s_waitcnt lgkmcnt(0)
	v_mov_b32_e32 v120, v110
	v_mfma_f32_32x32x16_bf16 v[80:95], v[106:109], v[2:5], v[80:95]
	ds_read2st64_b64 v[106:109], v15 offset0:40 offset1:48
	v_mov_b32_e32 v121, v111
	s_waitcnt lgkmcnt(0)
	v_mov_b32_e32 v118, v106
	v_mov_b32_e32 v119, v107
	v_mov_b32_e32 v110, v108
	v_mov_b32_e32 v111, v109
	ds_read_b64 v[106:107], v15 offset:28672
	ds_read_b64 v[108:109], v105 offset:28672
	v_add3_u32 v15, v104, v203, v190
	v_mfma_f32_32x32x16_bf16 v[64:79], v[118:121], v[2:5], v[64:79]
	v_mfma_f32_32x32x16_bf16 v[48:63], v[110:113], v[2:5], v[48:63]
	s_waitcnt lgkmcnt(0)
	v_mfma_f32_32x32x16_bf16 v[32:47], v[106:109], v[2:5], v[32:47]
	v_cvt_pk_bf16_f32 v3, v98, v99
	ds_read_b64 v[98:99], v15 offset:16384
	v_add3_u32 v15, v104, v216, v190
	v_cvt_pk_bf16_f32 v4, v100, v101
	ds_read_b64 v[100:101], v15 offset:16384
	v_cvt_pk_bf16_f32 v2, v114, v116
	v_cvt_pk_bf16_f32 v5, v102, v103
	v_add_u32_e32 v15, v9, v203
	v_add_u32_e32 v102, v9, v216
	s_waitcnt lgkmcnt(0)
	v_mfma_f32_32x32x16_bf16 v[80:95], v[98:101], v[2:5], v[80:95]
	ds_read2st64_b64 v[98:101], v15 offset0:40 offset1:48
	ds_read2st64_b64 v[106:109], v102 offset0:40 offset1:48
	s_waitcnt lgkmcnt(1)
	v_mov_b32_e32 v110, v98
	v_mov_b32_e32 v111, v99
	s_waitcnt lgkmcnt(0)
	v_mov_b32_e32 v112, v106
	v_mov_b32_e32 v113, v107
	v_mov_b32_e32 v106, v100
	v_mov_b32_e32 v107, v101
	ds_read_b64 v[98:99], v15 offset:28672
	ds_read_b64 v[100:101], v102 offset:28672
	v_mfma_f32_32x32x16_bf16 v[64:79], v[110:113], v[2:5], v[64:79]
	v_add_u32_e32 v15, v9, v218
	v_mfma_f32_32x32x16_bf16 v[48:63], v[106:109], v[2:5], v[48:63]
	s_waitcnt lgkmcnt(0)
	v_mfma_f32_32x32x16_bf16 v[32:47], v[98:101], v[2:5], v[32:47]
	v_cvt_pk_bf16_f32 v2, v8, v10
	v_add3_u32 v8, v104, v217, v190
	v_cvt_pk_bf16_f32 v3, v11, v12
	ds_read_b64 v[10:11], v8 offset:16384
	v_add3_u32 v8, v104, v218, v190
	v_cvt_pk_bf16_f32 v4, v13, v14
	ds_read_b64 v[12:13], v8 offset:16384
	v_cvt_pk_bf16_f32 v5, v96, v97
	v_add_u32_e32 v14, v9, v217
	ds_read2st64_b64 v[96:99], v15 offset0:40 offset1:48
	s_waitcnt lgkmcnt(1)
	v_mfma_f32_32x32x16_bf16 v[80:95], v[10:13], v[2:5], v[80:95]
	ds_read2st64_b64 v[10:13], v14 offset0:40 offset1:48
	s_waitcnt lgkmcnt(0)
	v_mov_b32_e32 v8, v10
	v_mov_b32_e32 v9, v11
	v_mov_b32_e32 v10, v96
	v_mov_b32_e32 v11, v97
	v_mov_b32_e32 v96, v12
	v_mov_b32_e32 v97, v13
	v_mfma_f32_32x32x16_bf16 v[64:79], v[8:11], v[2:5], v[64:79]
	ds_read_b64 v[8:9], v14 offset:28672
	ds_read_b64 v[10:11], v15 offset:28672
	v_mfma_f32_32x32x16_bf16 v[48:63], v[96:99], v[2:5], v[48:63]
	s_waitcnt lgkmcnt(0)
	v_mfma_f32_32x32x16_bf16 v[32:47], v[8:11], v[2:5], v[32:47]

.LBB0_1369:
	s_or_b32 s82, s34, 1
	s_lshl_b64 s[4:5], s[82:83], 7
	v_add_u32_e32 v2, 0x8000, v202
	s_add_u32 s4, s8, s4
	v_mov_b32_e32 v0, v198
	v_readfirstlane_b32 s17, v2
	s_addc_u32 s5, s9, s5
	s_mov_b32 m0, s17
	v_add_u32_e32 v2, 0x9000, v202
	global_load_lds_dwordx4 v0, s[4:5]
	v_mov_b32_e32 v0, v199
	v_readfirstlane_b32 s17, v2
	s_mov_b32 m0, s17
	v_add_u32_e32 v2, 0xa000, v202
	global_load_lds_dwordx4 v0, s[4:5]
	v_mov_b32_e32 v0, v200
	v_readfirstlane_b32 s17, v2
	v_add_u32_e32 v2, 0xb000, v202
	s_mov_b32 m0, s17
	v_readfirstlane_b32 s17, v2
	global_load_lds_dwordx4 v0, s[4:5]
	v_mov_b32_e32 v0, v201
	s_mov_b32 m0, s17
	s_nop 0
	global_load_lds_dwordx4 v0, s[4:5]
	v_cmp_lt_i32_e64 s[4:5], s34, v226
	s_and_saveexec_b64 s[22:23], s[4:5]
	s_cbranch_execz .LBB0_1371
	ds_read_b128 v[2:5], v222 offset:24576
	ds_read_b128 v[6:9], v222 offset:28672
	ds_read_b128 v[10:13], v223 offset:24576
	ds_read_b128 v[244:247], v223 offset:28672
	s_waitcnt lgkmcnt(3)
	v_mfma_f32_32x32x16_bf16 v[128:143], v[2:5], v[160:163], v[16:31]
	ds_read_b128 v[2:5], v224 offset:24576
	s_waitcnt lgkmcnt(3)
	v_mfma_f32_32x32x16_bf16 v[144:159], v[6:9], v[160:163], v[16:31]
	ds_read_b128 v[6:9], v224 offset:28672
	s_waitcnt lgkmcnt(3)
	v_mfma_f32_32x32x16_bf16 v[128:143], v[10:13], v[164:167], v[128:143]
	ds_read_b128 v[10:13], v225 offset:24576
	s_waitcnt lgkmcnt(3)
	v_mfma_f32_32x32x16_bf16 v[144:159], v[244:247], v[164:167], v[144:159]
	ds_read_b128 v[244:247], v225 offset:28672
	s_waitcnt lgkmcnt(3)
	v_mfma_f32_32x32x16_bf16 v[128:143], v[2:5], v[168:171], v[128:143]
	s_waitcnt lgkmcnt(2)
	v_mfma_f32_32x32x16_bf16 v[144:159], v[6:9], v[168:171], v[144:159]
	s_waitcnt lgkmcnt(1)
	v_mfma_f32_32x32x16_bf16 v[128:143], v[10:13], v[172:175], v[128:143]
	s_waitcnt lgkmcnt(0)
	v_mfma_f32_32x32x16_bf16 v[144:159], v[244:247], v[172:175], v[144:159]

.LBB0_1381:
	ds_read_b128 v[2:5], v222
	ds_read_b128 v[6:9], v222 offset:4096
	ds_read_b128 v[10:13], v223
	ds_read_b128 v[244:247], v223 offset:4096
	s_waitcnt lgkmcnt(3)
	v_mfma_f32_32x32x16_bf16 v[32:47], v[2:5], v[160:163], v[16:31]
	ds_read_b128 v[2:5], v224
	s_waitcnt lgkmcnt(3)
	v_mfma_f32_32x32x16_bf16 v[48:63], v[6:9], v[160:163], v[16:31]
	ds_read_b128 v[6:9], v224 offset:4096
	s_waitcnt lgkmcnt(3)
	v_mfma_f32_32x32x16_bf16 v[32:47], v[10:13], v[164:167], v[32:47]
	ds_read_b128 v[10:13], v225
	s_waitcnt lgkmcnt(3)
	v_mfma_f32_32x32x16_bf16 v[48:63], v[244:247], v[164:167], v[48:63]
	ds_read_b128 v[244:247], v225 offset:4096
	s_waitcnt lgkmcnt(3)
	v_mfma_f32_32x32x16_bf16 v[32:47], v[2:5], v[168:171], v[32:47]
	s_waitcnt lgkmcnt(2)
	v_mfma_f32_32x32x16_bf16 v[48:63], v[6:9], v[168:171], v[48:63]
	s_waitcnt lgkmcnt(1)
	v_mfma_f32_32x32x16_bf16 v[32:47], v[10:13], v[172:175], v[32:47]
	s_waitcnt lgkmcnt(0)
	v_mfma_f32_32x32x16_bf16 v[48:63], v[244:247], v[172:175], v[48:63]
	s_or_b64 exec, exec, s[20:21]
	s_and_saveexec_b64 s[20:21], s[4:5]
	s_cbranch_execnz .LBB0_1385
	s_branch .LBB0_1386

.LBB0_1411:
	s_or_b32 s82, s31, 1
	s_lshl_b64 s[4:5], s[82:83], 7
	v_add_u32_e32 v2, 0x8000, v200
	s_add_u32 s4, s8, s4
	v_mov_b32_e32 v0, v196
	v_readfirstlane_b32 s17, v2
	s_addc_u32 s5, s9, s5
	s_mov_b32 m0, s17
	v_add_u32_e32 v2, 0x9000, v200
	global_load_lds_dwordx4 v0, s[4:5]
	v_mov_b32_e32 v0, v197
	v_readfirstlane_b32 s17, v2
	s_mov_b32 m0, s17
	v_add_u32_e32 v2, 0xa000, v200
	global_load_lds_dwordx4 v0, s[4:5]
	v_mov_b32_e32 v0, v198
	v_readfirstlane_b32 s17, v2
	v_add_u32_e32 v2, 0xb000, v200
	s_mov_b32 m0, s17
	v_readfirstlane_b32 s17, v2
	global_load_lds_dwordx4 v0, s[4:5]
	v_mov_b32_e32 v0, v199
	s_mov_b32 m0, s17
	s_nop 0
	global_load_lds_dwordx4 v0, s[4:5]
	v_cmp_lt_i32_e64 s[4:5], s31, v225
	s_and_saveexec_b64 s[22:23], s[4:5]
	s_cbranch_execz .LBB0_1413
	ds_read_b128 v[2:5], v220 offset:24576
	ds_read_b128 v[6:9], v220 offset:28672
	ds_read_b128 v[10:13], v221 offset:24576
	ds_read_b128 v[244:247], v221 offset:28672
	s_waitcnt lgkmcnt(3)
	v_mfma_f32_32x32x16_bf16 v[128:143], v[2:5], v[160:163], v[16:31]
	ds_read_b128 v[2:5], v222 offset:24576
	s_waitcnt lgkmcnt(3)
	v_mfma_f32_32x32x16_bf16 v[144:159], v[6:9], v[160:163], v[16:31]
	ds_read_b128 v[6:9], v222 offset:28672
	s_waitcnt lgkmcnt(3)
	v_mfma_f32_32x32x16_bf16 v[128:143], v[10:13], v[164:167], v[128:143]
	ds_read_b128 v[10:13], v223 offset:24576
	s_waitcnt lgkmcnt(3)
	v_mfma_f32_32x32x16_bf16 v[144:159], v[244:247], v[164:167], v[144:159]
	ds_read_b128 v[244:247], v223 offset:28672
	s_waitcnt lgkmcnt(3)
	v_mfma_f32_32x32x16_bf16 v[128:143], v[2:5], v[168:171], v[128:143]
	s_waitcnt lgkmcnt(2)
	v_mfma_f32_32x32x16_bf16 v[144:159], v[6:9], v[168:171], v[144:159]
	s_waitcnt lgkmcnt(1)
	v_mfma_f32_32x32x16_bf16 v[128:143], v[10:13], v[172:175], v[128:143]
	s_waitcnt lgkmcnt(0)
	v_mfma_f32_32x32x16_bf16 v[144:159], v[244:247], v[172:175], v[144:159]

.LBB0_1423:
	ds_read_b128 v[2:5], v220
	ds_read_b128 v[6:9], v220 offset:4096
	ds_read_b128 v[10:13], v221
	ds_read_b128 v[244:247], v221 offset:4096
	s_waitcnt lgkmcnt(3)
	v_mfma_f32_32x32x16_bf16 v[80:95], v[2:5], v[160:163], v[16:31]
	ds_read_b128 v[2:5], v222
	s_waitcnt lgkmcnt(3)
	v_mfma_f32_32x32x16_bf16 v[96:111], v[6:9], v[160:163], v[16:31]
	ds_read_b128 v[6:9], v222 offset:4096
	s_waitcnt lgkmcnt(3)
	v_mfma_f32_32x32x16_bf16 v[80:95], v[10:13], v[164:167], v[80:95]
	ds_read_b128 v[10:13], v223
	s_waitcnt lgkmcnt(3)
	v_mfma_f32_32x32x16_bf16 v[96:111], v[244:247], v[164:167], v[96:111]
	ds_read_b128 v[244:247], v223 offset:4096
	s_waitcnt lgkmcnt(3)
	v_mfma_f32_32x32x16_bf16 v[80:95], v[2:5], v[168:171], v[80:95]
	s_waitcnt lgkmcnt(2)
	v_mfma_f32_32x32x16_bf16 v[96:111], v[6:9], v[168:171], v[96:111]
	s_waitcnt lgkmcnt(1)
	v_mfma_f32_32x32x16_bf16 v[80:95], v[10:13], v[172:175], v[80:95]
	s_waitcnt lgkmcnt(0)
	v_mfma_f32_32x32x16_bf16 v[96:111], v[244:247], v[172:175], v[96:111]
	s_or_b64 exec, exec, s[20:21]
	s_and_saveexec_b64 s[20:21], s[4:5]
	s_cbranch_execnz .LBB0_1427
	s_branch .LBB0_1428
